# ffn_in SwiGLU epilogue hand-written: packed f32 ops on register pairs (same per-element operation order), two pairs interleaved (no hazard nops), 32-bit saddr store offsets
# speedup vs baseline: 1.0025x; 1.0025x over previous
; __device__ __forceinline__ float siluf_(float x) { return x * __builtin_amdgcn_rcpf(1.f + __expf(-x)); }
;     ...
;     if (MODE == 4) {
;       u16* act = (u16*)(ws + OFF_RA);
;       uint2 opend4[2];
; #pragma unroll
;       for (int bj = 0; bj < 2; ++bj)
; #pragma unroll
;         for (int m = 0; m < 4; ++m)
; #pragma unroll
;           for (int n = 0; n < 2; ++n) {
;             int lane_i = lane_e;
;             asm volatile("" : "+v"(lane_i));
;             const int fr = lane_i & 15, fq = lane_i >> 4;
;             const int nc = tn * 128 + wr * 64 + m * 16 + fq * 4;
;             const int tok = bcol + bj * 128 + wc * 32 + n * 16 + fr;
;             f32x4 g = acc[0][bj][m][n], up = acc[1][bj][m][n];
;             uint2 o;
;             o.x = pk2(siluf_(g[0]) * up[0], siluf_(g[1]) * up[1]);
;             o.y = pk2(siluf_(g[2]) * up[2], siluf_(g[3]) * up[3]);
;             if ((m & 1) == 0) opend4[n] = o;
;             else {
;               const int ncw = tn * 128 + wr * 64 + ((m & ~1) + (fq & 1)) * 16 + (fq & ~1) * 4;
;               *(uint4*)(act + (size_t)tok * DFF + ncw) = swap_pair(opend4[n], o);
;             }
;           }
.LBB0_1018:
	v_mov_b32_e32 v250, 0xbfb8aa3b
	v_mov_b32_e32 v252, 1.0
	s_or_b32 s0, s27, s54
	s_lshl_b32 s1, s28, 7
	s_add_i32 s1, s1, s49
	s_movk_i32 s3, 0x2c00
	v_and_or_b32 v132, v134, 15, s0
	v_and_or_b32 v133, v134, 16, s1
	v_ashrrev_i32_e32 v140, 2, v134
	v_and_b32_e32 v140, -8, v140
	v_add_u32_e32 v133, v133, v140
	v_lshlrev_b32_e32 v133, 1, v133
	v_mad_u32_u24 v247, v132, s3, v133
	v_add_u32_e32 v248, 0x2c000, v247
	v_add_u32_e32 v249, 0x160000, v247
	v_add_u32_e32 v254, 0x18c000, v247
	v_pk_mul_f32 v[132:133], v[124:125], v[250:251] op_sel_hi:[1,0]
	v_pk_mul_f32 v[140:141], v[126:127], v[250:251] op_sel_hi:[1,0]
	v_exp_f32_e32 v132, v132
	v_exp_f32_e32 v133, v133
	v_exp_f32_e32 v140, v140
	v_exp_f32_e32 v141, v141
	v_pk_add_f32 v[132:133], v[132:133], v[252:253] op_sel_hi:[1,0]
	v_pk_add_f32 v[140:141], v[140:141], v[252:253] op_sel_hi:[1,0]
	v_rcp_f32_e32 v132, v132
	v_rcp_f32_e32 v133, v133
	v_rcp_f32_e32 v140, v140
	v_rcp_f32_e32 v141, v141
	v_pk_mul_f32 v[124:125], v[124:125], v[132:133]
	v_pk_mul_f32 v[126:127], v[126:127], v[140:141]
	v_pk_mul_f32 v[124:125], v[124:125], v[120:121]
	v_pk_mul_f32 v[126:127], v[126:127], v[122:123]
	v_cvt_pk_bf16_f32 v124, v124, v125
	v_cvt_pk_bf16_f32 v125, v126, v127
	v_pk_mul_f32 v[132:133], v[108:109], v[250:251] op_sel_hi:[1,0]
	v_pk_mul_f32 v[140:141], v[110:111], v[250:251] op_sel_hi:[1,0]
	v_exp_f32_e32 v132, v132
	v_exp_f32_e32 v133, v133
	v_exp_f32_e32 v140, v140
	v_exp_f32_e32 v141, v141
	v_pk_add_f32 v[132:133], v[132:133], v[252:253] op_sel_hi:[1,0]
	v_pk_add_f32 v[140:141], v[140:141], v[252:253] op_sel_hi:[1,0]
	v_rcp_f32_e32 v132, v132
	v_rcp_f32_e32 v133, v133
	v_rcp_f32_e32 v140, v140
	v_rcp_f32_e32 v141, v141
	v_pk_mul_f32 v[108:109], v[108:109], v[132:133]
	v_pk_mul_f32 v[110:111], v[110:111], v[140:141]
	v_pk_mul_f32 v[108:109], v[108:109], v[104:105]
	v_pk_mul_f32 v[110:111], v[110:111], v[106:107]
	v_cvt_pk_bf16_f32 v126, v108, v109
	v_cvt_pk_bf16_f32 v127, v110, v111
	s_nop 1
	v_permlane16_swap_b32_e32 v125, v127
	v_permlane16_swap_b32_e32 v124, v126
	global_store_dwordx4 v247, v[124:127], s[66:67]
	v_pk_mul_f32 v[132:133], v[116:117], v[250:251] op_sel_hi:[1,0]
	v_pk_mul_f32 v[140:141], v[118:119], v[250:251] op_sel_hi:[1,0]
	v_exp_f32_e32 v132, v132
	v_exp_f32_e32 v133, v133
	v_exp_f32_e32 v140, v140
	v_exp_f32_e32 v141, v141
	v_pk_add_f32 v[132:133], v[132:133], v[252:253] op_sel_hi:[1,0]
	v_pk_add_f32 v[140:141], v[140:141], v[252:253] op_sel_hi:[1,0]
	v_rcp_f32_e32 v132, v132
	v_rcp_f32_e32 v133, v133
	v_rcp_f32_e32 v140, v140
	v_rcp_f32_e32 v141, v141
	v_pk_mul_f32 v[116:117], v[116:117], v[132:133]
	v_pk_mul_f32 v[118:119], v[118:119], v[140:141]
	v_pk_mul_f32 v[116:117], v[116:117], v[112:113]
	v_pk_mul_f32 v[118:119], v[118:119], v[114:115]
	v_cvt_pk_bf16_f32 v116, v116, v117
	v_cvt_pk_bf16_f32 v117, v118, v119
	v_pk_mul_f32 v[132:133], v[100:101], v[250:251] op_sel_hi:[1,0]
	v_pk_mul_f32 v[140:141], v[102:103], v[250:251] op_sel_hi:[1,0]
	v_exp_f32_e32 v132, v132
	v_exp_f32_e32 v133, v133
	v_exp_f32_e32 v140, v140
	v_exp_f32_e32 v141, v141
	v_pk_add_f32 v[132:133], v[132:133], v[252:253] op_sel_hi:[1,0]
	v_pk_add_f32 v[140:141], v[140:141], v[252:253] op_sel_hi:[1,0]
	v_rcp_f32_e32 v132, v132
	v_rcp_f32_e32 v133, v133
	v_rcp_f32_e32 v140, v140
	v_rcp_f32_e32 v141, v141
	v_pk_mul_f32 v[100:101], v[100:101], v[132:133]
	v_pk_mul_f32 v[102:103], v[102:103], v[140:141]
	v_pk_mul_f32 v[100:101], v[100:101], v[96:97]
	v_pk_mul_f32 v[102:103], v[102:103], v[98:99]
	v_cvt_pk_bf16_f32 v118, v100, v101
	v_cvt_pk_bf16_f32 v119, v102, v103
	s_nop 1
	v_permlane16_swap_b32_e32 v117, v119
	v_permlane16_swap_b32_e32 v116, v118
	global_store_dwordx4 v248, v[116:119], s[66:67]
	v_pk_mul_f32 v[132:133], v[92:93], v[250:251] op_sel_hi:[1,0]
	v_pk_mul_f32 v[140:141], v[94:95], v[250:251] op_sel_hi:[1,0]
	v_exp_f32_e32 v132, v132
	v_exp_f32_e32 v133, v133
	v_exp_f32_e32 v140, v140
	v_exp_f32_e32 v141, v141
	v_pk_add_f32 v[132:133], v[132:133], v[252:253] op_sel_hi:[1,0]
	v_pk_add_f32 v[140:141], v[140:141], v[252:253] op_sel_hi:[1,0]
	v_rcp_f32_e32 v132, v132
	v_rcp_f32_e32 v133, v133
	v_rcp_f32_e32 v140, v140
	v_rcp_f32_e32 v141, v141
	v_pk_mul_f32 v[92:93], v[92:93], v[132:133]
	v_pk_mul_f32 v[94:95], v[94:95], v[140:141]
	v_pk_mul_f32 v[92:93], v[92:93], v[88:89]
	v_pk_mul_f32 v[94:95], v[94:95], v[90:91]
	v_cvt_pk_bf16_f32 v92, v92, v93
	v_cvt_pk_bf16_f32 v93, v94, v95
	v_pk_mul_f32 v[132:133], v[76:77], v[250:251] op_sel_hi:[1,0]
	v_pk_mul_f32 v[140:141], v[78:79], v[250:251] op_sel_hi:[1,0]
	v_exp_f32_e32 v132, v132
	v_exp_f32_e32 v133, v133
	v_exp_f32_e32 v140, v140
	v_exp_f32_e32 v141, v141
	v_pk_add_f32 v[132:133], v[132:133], v[252:253] op_sel_hi:[1,0]
	v_pk_add_f32 v[140:141], v[140:141], v[252:253] op_sel_hi:[1,0]
	v_rcp_f32_e32 v132, v132
	v_rcp_f32_e32 v133, v133
	v_rcp_f32_e32 v140, v140
	v_rcp_f32_e32 v141, v141
	v_pk_mul_f32 v[76:77], v[76:77], v[132:133]
	v_pk_mul_f32 v[78:79], v[78:79], v[140:141]
	v_pk_mul_f32 v[76:77], v[76:77], v[72:73]
	v_pk_mul_f32 v[78:79], v[78:79], v[74:75]
	v_cvt_pk_bf16_f32 v94, v76, v77
	v_cvt_pk_bf16_f32 v95, v78, v79
	s_nop 1
	v_permlane16_swap_b32_e32 v93, v95
	v_permlane16_swap_b32_e32 v92, v94
	global_store_dwordx4 v247, v[92:95], s[66:67] offset:64
	v_pk_mul_f32 v[132:133], v[84:85], v[250:251] op_sel_hi:[1,0]
	v_pk_mul_f32 v[140:141], v[86:87], v[250:251] op_sel_hi:[1,0]
	v_exp_f32_e32 v132, v132
	v_exp_f32_e32 v133, v133
	v_exp_f32_e32 v140, v140
	v_exp_f32_e32 v141, v141
	v_pk_add_f32 v[132:133], v[132:133], v[252:253] op_sel_hi:[1,0]
	v_pk_add_f32 v[140:141], v[140:141], v[252:253] op_sel_hi:[1,0]
	v_rcp_f32_e32 v132, v132
; __device__ __forceinline__ float siluf_(float x) { return x * __builtin_amdgcn_rcpf(1.f + __expf(-x)); }
;     ...
;             int lane_i = lane_e;
;             asm volatile("" : "+v"(lane_i));
;             const int fr = lane_i & 15, fq = lane_i >> 4;
;             const int nc = tn * 128 + wr * 64 + m * 16 + fq * 4;
;             const int tok = bcol + bj * 128 + wc * 32 + n * 16 + fr;
;             f32x4 g = acc[0][bj][m][n], up = acc[1][bj][m][n];
;             uint2 o;
;             o.x = pk2(siluf_(g[0]) * up[0], siluf_(g[1]) * up[1]);
;             o.y = pk2(siluf_(g[2]) * up[2], siluf_(g[3]) * up[3]);
;             if ((m & 1) == 0) opend4[n] = o;
;             else {
;               const int ncw = tn * 128 + wr * 64 + ((m & ~1) + (fq & 1)) * 16 + (fq & ~1) * 4;
;               *(uint4*)(act + (size_t)tok * DFF + ncw) = swap_pair(opend4[n], o);
	v_rcp_f32_e32 v133, v133
	v_rcp_f32_e32 v140, v140
	v_rcp_f32_e32 v141, v141
	v_pk_mul_f32 v[84:85], v[84:85], v[132:133]
	v_pk_mul_f32 v[86:87], v[86:87], v[140:141]
	v_pk_mul_f32 v[84:85], v[84:85], v[80:81]
	v_pk_mul_f32 v[86:87], v[86:87], v[82:83]
	v_cvt_pk_bf16_f32 v84, v84, v85
	v_cvt_pk_bf16_f32 v85, v86, v87
	v_pk_mul_f32 v[132:133], v[68:69], v[250:251] op_sel_hi:[1,0]
	v_pk_mul_f32 v[140:141], v[70:71], v[250:251] op_sel_hi:[1,0]
	v_exp_f32_e32 v132, v132
	v_exp_f32_e32 v133, v133
	v_exp_f32_e32 v140, v140
	v_exp_f32_e32 v141, v141
	v_pk_add_f32 v[132:133], v[132:133], v[252:253] op_sel_hi:[1,0]
	v_pk_add_f32 v[140:141], v[140:141], v[252:253] op_sel_hi:[1,0]
	v_rcp_f32_e32 v132, v132
	v_rcp_f32_e32 v133, v133
	v_rcp_f32_e32 v140, v140
	v_rcp_f32_e32 v141, v141
	v_pk_mul_f32 v[68:69], v[68:69], v[132:133]
	v_pk_mul_f32 v[70:71], v[70:71], v[140:141]
	v_pk_mul_f32 v[68:69], v[68:69], v[64:65]
	v_pk_mul_f32 v[70:71], v[70:71], v[66:67]
	v_cvt_pk_bf16_f32 v86, v68, v69
	v_cvt_pk_bf16_f32 v87, v70, v71
	s_nop 1
	v_permlane16_swap_b32_e32 v85, v87
	v_permlane16_swap_b32_e32 v84, v86
	global_store_dwordx4 v248, v[84:87], s[66:67] offset:64
	v_pk_mul_f32 v[132:133], v[60:61], v[250:251] op_sel_hi:[1,0]
	v_pk_mul_f32 v[140:141], v[62:63], v[250:251] op_sel_hi:[1,0]
	v_exp_f32_e32 v132, v132
	v_exp_f32_e32 v133, v133
	v_exp_f32_e32 v140, v140
	v_exp_f32_e32 v141, v141
	v_pk_add_f32 v[132:133], v[132:133], v[252:253] op_sel_hi:[1,0]
	v_pk_add_f32 v[140:141], v[140:141], v[252:253] op_sel_hi:[1,0]
	v_rcp_f32_e32 v132, v132
	v_rcp_f32_e32 v133, v133
	v_rcp_f32_e32 v140, v140
	v_rcp_f32_e32 v141, v141
	v_pk_mul_f32 v[60:61], v[60:61], v[132:133]
	v_pk_mul_f32 v[62:63], v[62:63], v[140:141]
	v_pk_mul_f32 v[60:61], v[60:61], v[56:57]
	v_pk_mul_f32 v[62:63], v[62:63], v[58:59]
	v_cvt_pk_bf16_f32 v60, v60, v61
	v_cvt_pk_bf16_f32 v61, v62, v63
	v_pk_mul_f32 v[132:133], v[44:45], v[250:251] op_sel_hi:[1,0]
	v_pk_mul_f32 v[140:141], v[46:47], v[250:251] op_sel_hi:[1,0]
	v_exp_f32_e32 v132, v132
	v_exp_f32_e32 v133, v133
	v_exp_f32_e32 v140, v140
	v_exp_f32_e32 v141, v141
	v_pk_add_f32 v[132:133], v[132:133], v[252:253] op_sel_hi:[1,0]
	v_pk_add_f32 v[140:141], v[140:141], v[252:253] op_sel_hi:[1,0]
	v_rcp_f32_e32 v132, v132
	v_rcp_f32_e32 v133, v133
	v_rcp_f32_e32 v140, v140
	v_rcp_f32_e32 v141, v141
	v_pk_mul_f32 v[44:45], v[44:45], v[132:133]
	v_pk_mul_f32 v[46:47], v[46:47], v[140:141]
	v_pk_mul_f32 v[44:45], v[44:45], v[40:41]
	v_pk_mul_f32 v[46:47], v[46:47], v[42:43]
	v_cvt_pk_bf16_f32 v62, v44, v45
	v_cvt_pk_bf16_f32 v63, v46, v47
	s_nop 1
	v_permlane16_swap_b32_e32 v61, v63
	v_permlane16_swap_b32_e32 v60, v62
	global_store_dwordx4 v249, v[60:63], s[66:67]
	v_pk_mul_f32 v[132:133], v[52:53], v[250:251] op_sel_hi:[1,0]
	v_pk_mul_f32 v[140:141], v[54:55], v[250:251] op_sel_hi:[1,0]
	v_exp_f32_e32 v132, v132
	v_exp_f32_e32 v133, v133
	v_exp_f32_e32 v140, v140
	v_exp_f32_e32 v141, v141
	v_pk_add_f32 v[132:133], v[132:133], v[252:253] op_sel_hi:[1,0]
	v_pk_add_f32 v[140:141], v[140:141], v[252:253] op_sel_hi:[1,0]
	v_rcp_f32_e32 v132, v132
	v_rcp_f32_e32 v133, v133
	v_rcp_f32_e32 v140, v140
	v_rcp_f32_e32 v141, v141
	v_pk_mul_f32 v[52:53], v[52:53], v[132:133]
	v_pk_mul_f32 v[54:55], v[54:55], v[140:141]
	v_pk_mul_f32 v[52:53], v[52:53], v[48:49]
	v_pk_mul_f32 v[54:55], v[54:55], v[50:51]
	v_cvt_pk_bf16_f32 v52, v52, v53
	v_cvt_pk_bf16_f32 v53, v54, v55
	v_pk_mul_f32 v[132:133], v[36:37], v[250:251] op_sel_hi:[1,0]
	v_pk_mul_f32 v[140:141], v[38:39], v[250:251] op_sel_hi:[1,0]
	v_exp_f32_e32 v132, v132
	v_exp_f32_e32 v133, v133
	v_exp_f32_e32 v140, v140
	v_exp_f32_e32 v141, v141
	v_pk_add_f32 v[132:133], v[132:133], v[252:253] op_sel_hi:[1,0]
; __device__ __forceinline__ float siluf_(float x) { return x * __builtin_amdgcn_rcpf(1.f + __expf(-x)); }
;     ...
;             int lane_i = lane_e;
;             asm volatile("" : "+v"(lane_i));
;             const int fr = lane_i & 15, fq = lane_i >> 4;
;             const int nc = tn * 128 + wr * 64 + m * 16 + fq * 4;
;             const int tok = bcol + bj * 128 + wc * 32 + n * 16 + fr;
;             f32x4 g = acc[0][bj][m][n], up = acc[1][bj][m][n];
;             uint2 o;
;             o.x = pk2(siluf_(g[0]) * up[0], siluf_(g[1]) * up[1]);
;             o.y = pk2(siluf_(g[2]) * up[2], siluf_(g[3]) * up[3]);
;             if ((m & 1) == 0) opend4[n] = o;
;             else {
;               const int ncw = tn * 128 + wr * 64 + ((m & ~1) + (fq & 1)) * 16 + (fq & ~1) * 4;
;               *(uint4*)(act + (size_t)tok * DFF + ncw) = swap_pair(opend4[n], o);
;             }
;           }
;     ...
;     asm volatile("s_waitcnt vmcnt(0)" ::: "memory");
;     if (has_next && wr == 1) __builtin_amdgcn_s_barrier();
	v_pk_add_f32 v[140:141], v[140:141], v[252:253] op_sel_hi:[1,0]
	v_rcp_f32_e32 v132, v132
	v_rcp_f32_e32 v133, v133
	v_rcp_f32_e32 v140, v140
	v_rcp_f32_e32 v141, v141
	v_pk_mul_f32 v[36:37], v[36:37], v[132:133]
	v_pk_mul_f32 v[38:39], v[38:39], v[140:141]
	v_pk_mul_f32 v[36:37], v[36:37], v[32:33]
	v_pk_mul_f32 v[38:39], v[38:39], v[34:35]
	v_cvt_pk_bf16_f32 v54, v36, v37
	v_cvt_pk_bf16_f32 v55, v38, v39
	s_nop 1
	v_permlane16_swap_b32_e32 v53, v55
	v_permlane16_swap_b32_e32 v52, v54
	global_store_dwordx4 v254, v[52:55], s[66:67]
	v_pk_mul_f32 v[132:133], v[28:29], v[250:251] op_sel_hi:[1,0]
	v_pk_mul_f32 v[140:141], v[30:31], v[250:251] op_sel_hi:[1,0]
	v_exp_f32_e32 v132, v132
	v_exp_f32_e32 v133, v133
	v_exp_f32_e32 v140, v140
	v_exp_f32_e32 v141, v141
	v_pk_add_f32 v[132:133], v[132:133], v[252:253] op_sel_hi:[1,0]
	v_pk_add_f32 v[140:141], v[140:141], v[252:253] op_sel_hi:[1,0]
	v_rcp_f32_e32 v132, v132
	v_rcp_f32_e32 v133, v133
	v_rcp_f32_e32 v140, v140
	v_rcp_f32_e32 v141, v141
	v_pk_mul_f32 v[28:29], v[28:29], v[132:133]
	v_pk_mul_f32 v[30:31], v[30:31], v[140:141]
	v_pk_mul_f32 v[28:29], v[28:29], v[24:25]
	v_pk_mul_f32 v[30:31], v[30:31], v[26:27]
	v_cvt_pk_bf16_f32 v28, v28, v29
	v_cvt_pk_bf16_f32 v29, v30, v31
	v_pk_mul_f32 v[132:133], v[12:13], v[250:251] op_sel_hi:[1,0]
	v_pk_mul_f32 v[140:141], v[14:15], v[250:251] op_sel_hi:[1,0]
	v_exp_f32_e32 v132, v132
	v_exp_f32_e32 v133, v133
	v_exp_f32_e32 v140, v140
	v_exp_f32_e32 v141, v141
	v_pk_add_f32 v[132:133], v[132:133], v[252:253] op_sel_hi:[1,0]
	v_pk_add_f32 v[140:141], v[140:141], v[252:253] op_sel_hi:[1,0]
	v_rcp_f32_e32 v132, v132
	v_rcp_f32_e32 v133, v133
	v_rcp_f32_e32 v140, v140
	v_rcp_f32_e32 v141, v141
	v_pk_mul_f32 v[12:13], v[12:13], v[132:133]
	v_pk_mul_f32 v[14:15], v[14:15], v[140:141]
	v_pk_mul_f32 v[12:13], v[12:13], v[8:9]
	v_pk_mul_f32 v[14:15], v[14:15], v[10:11]
	v_cvt_pk_bf16_f32 v30, v12, v13
	v_cvt_pk_bf16_f32 v31, v14, v15
	s_nop 1
	v_permlane16_swap_b32_e32 v29, v31
	v_permlane16_swap_b32_e32 v28, v30
	global_store_dwordx4 v249, v[28:31], s[66:67] offset:64
	v_pk_mul_f32 v[132:133], v[20:21], v[250:251] op_sel_hi:[1,0]
	v_pk_mul_f32 v[140:141], v[22:23], v[250:251] op_sel_hi:[1,0]
	v_exp_f32_e32 v132, v132
	v_exp_f32_e32 v133, v133
	v_exp_f32_e32 v140, v140
	v_exp_f32_e32 v141, v141
	v_pk_add_f32 v[132:133], v[132:133], v[252:253] op_sel_hi:[1,0]
	v_pk_add_f32 v[140:141], v[140:141], v[252:253] op_sel_hi:[1,0]
	v_rcp_f32_e32 v132, v132
	v_rcp_f32_e32 v133, v133
	v_rcp_f32_e32 v140, v140
	v_rcp_f32_e32 v141, v141
	v_pk_mul_f32 v[20:21], v[20:21], v[132:133]
	v_pk_mul_f32 v[22:23], v[22:23], v[140:141]
	v_pk_mul_f32 v[20:21], v[20:21], v[16:17]
	v_pk_mul_f32 v[22:23], v[22:23], v[18:19]
	v_cvt_pk_bf16_f32 v20, v20, v21
	v_cvt_pk_bf16_f32 v21, v22, v23
	v_pk_mul_f32 v[132:133], v[4:5], v[250:251] op_sel_hi:[1,0]
	v_pk_mul_f32 v[140:141], v[6:7], v[250:251] op_sel_hi:[1,0]
	v_exp_f32_e32 v132, v132
	v_exp_f32_e32 v133, v133
	v_exp_f32_e32 v140, v140
	v_exp_f32_e32 v141, v141
	v_pk_add_f32 v[132:133], v[132:133], v[252:253] op_sel_hi:[1,0]
	v_pk_add_f32 v[140:141], v[140:141], v[252:253] op_sel_hi:[1,0]
	v_rcp_f32_e32 v132, v132
	v_rcp_f32_e32 v133, v133
	v_rcp_f32_e32 v140, v140
	v_rcp_f32_e32 v141, v141
	v_pk_mul_f32 v[4:5], v[4:5], v[132:133]
	v_pk_mul_f32 v[6:7], v[6:7], v[140:141]
	v_pk_mul_f32 v[4:5], v[4:5], v[0:1]
	v_pk_mul_f32 v[6:7], v[6:7], v[2:3]
	v_cvt_pk_bf16_f32 v22, v4, v5
	v_cvt_pk_bf16_f32 v23, v6, v7
	s_nop 1
	v_permlane16_swap_b32_e32 v21, v23
	v_permlane16_swap_b32_e32 v20, v22
	global_store_dwordx4 v254, v[20:23], s[66:67] offset:64
	s_waitcnt vmcnt(0)
	s_and_b64 s[0:1], s[56:57], s[8:9]
	s_andn2_b64 vcc, exec, s[0:1]
	s_cbranch_vccnz .LBB0_1009
	s_barrier
	s_branch .LBB0_1009
